# GEMM K loop: removed the s_setprio 0 / s_setprio 1 flip between the two 16-MFMA blocks of each super-phase (priority stays raised across both)
# speedup vs baseline: 1.0094x; 1.0024x over previous
; #define PG8_STAGE(bufoff, gbase, voff) do { _Pragma("unroll") for (int _i = 0; _i < 2; ++_i) \
;         __builtin_amdgcn_global_load_lds((const unsigned*)((const char*)(gbase) + (voff)[_i]), (PG8_LAS unsigned*)(lds + (bufoff) + ldsw + _i * 8192), 16, 0, 0); } while (0)
; #define PG8_LDA(dst, b, h) do { _Pragma("unroll") for (int m = 0; m < 4; ++m) _Pragma("unroll") for (int k = 0; k < 2; ++k) dst[m][k] = *(const PG8_LAS bf16x8*)(lds + PG8_SA(b, h) + aoff + m * 2048 + k * 1024); } while (0)
; #define PG8_LDB(dst, b, h) do { _Pragma("unroll") for (int n = 0; n < 2; ++n) _Pragma("unroll") for (int k = 0; k < 2; ++k) dst[n][k] = *(const PG8_LAS bf16x8*)(lds + PG8_SB(b, h) + boff + n * 2048 + k * 1024); } while (0)
; template <class Epi, class Sched, bool ALIGN_EPI = false, bool SP2 = false>
; __device__ __forceinline__ void gemm_phase(PG8_LAS unsigned char* lds, const Gemm g, const Sched& S, const Epi& E) {
;     ...
;         for (int t = 0; t < nt; t += 2) {
;             const bool last = (t == nt - 2);
;             const char* a1 = cA + (size_t)(t + 1) * kstep;
;             const char* a2 = last ? nA : cA + (size_t)(t + 2) * kstep; const char* b2 = last ? nB : cB + (size_t)(t + 2) * kstep;
;             const char* a3 = a2 + kstep; const char* b3 = b2 + kstep;
;             if (last && has_next) S.a_ready(nxt);
;             if constexpr (SP2) {
;             PG8_LDB(B0, 0, 0); PG8_LDB(B1, 0, 1); PG8_SCHED; PG8_LDA(At, 0, 0); PG8_STAGE(PG8_SA(1, 1), a1 + hstep, voffA);
;             PG8_WAIT_V(8); PG8_WAIT_L(0); PG8_BAR; PG8_MMA(0, 0, At, B0); PG8_MMA(0, 1, At, B1); PG8_BAR; PG8_SCHED;
;             PG8_LDA(At, 0, 1); PG8_STAGE(PG8_SB(0, 0), b2, voffB); PG8_STAGE(PG8_SB(0, 1), b2 + hstep, voffB); PG8_STAGE(PG8_SA(0, 0), a2, voffA);
;             PG8_WAIT_V(8); PG8_WAIT_L(0); PG8_BAR; PG8_MMA(1, 0, At, B0); PG8_MMA(1, 1, At, B1); PG8_BAR; PG8_SCHED;
;             PG8_LDB(B0, 1, 0); PG8_LDB(B1, 1, 1); PG8_SCHED; PG8_LDA(At, 1, 0); PG8_STAGE(PG8_SA(0, 1), a2 + hstep, voffA);
;             PG8_WAIT_V(8); PG8_WAIT_L(0); PG8_BAR; PG8_MMA(0, 0, At, B0); PG8_MMA(0, 1, At, B1); PG8_BAR; PG8_SCHED;
;             PG8_LDA(At, 1, 1); PG8_STAGE(PG8_SB(1, 0), b3, voffB); PG8_STAGE(PG8_SB(1, 1), b3 + hstep, voffB); PG8_STAGE(PG8_SA(1, 0), a3, voffA);
;             PG8_WAIT_V(8); PG8_WAIT_L(0); PG8_BAR; PG8_MMA(1, 0, At, B0); PG8_MMA(1, 1, At, B1); PG8_BAR; PG8_SCHED;
.LBB0_321:
	s_add_u32 s12, s16, 0x80
	s_addc_u32 s13, s17, 0
	s_add_u32 s16, s14, 0x100
	s_addc_u32 s17, s15, 0
	s_mov_b32 s14, 0
	s_nop 0
	s_nop 0
	s_waitcnt lgkmcnt(0)
	s_add_i32 s42, s14, 2
	s_add_u32 s43, s12, 0x80
	s_addc_u32 s15, s13, 0
	s_add_i32 s75, 0, 0x10000
	s_cmp_eq_u32 s25, s14
	s_cselect_b32 s15, s55, s15
	s_cselect_b32 s14, s54, s43
	s_cselect_b32 vcc_hi, s65, s17
	s_cselect_b32 vcc_lo, s64, s16
	s_add_i32 s43, 0, 0x14000
	v_add_u32_e32 v142, s75, v199
	v_add_u32_e32 v178, s43, v199
	ds_read_b128 v[130:133], v142
	ds_read_b128 v[134:137], v142 offset:1024
	ds_read_b128 v[138:141], v142 offset:2048
	ds_read_b128 v[142:145], v142 offset:3072
	ds_read_b128 v[170:173], v178
	ds_read_b128 v[174:177], v178 offset:1024
	ds_read_b128 v[202:205], v178 offset:2048
	ds_read_b128 v[206:209], v178 offset:3072
	v_lshl_add_u64 v[178:179], s[12:13], 0, v[166:167]
	s_add_i32 m0, s56, 0xc000
	ds_read_b128 v[210:213], v201
	ds_read_b128 v[214:217], v201 offset:1024
	ds_read_b128 v[218:221], v201 offset:2048
	ds_read_b128 v[222:225], v201 offset:3072
	ds_read_b128 v[226:229], v201 offset:4096
	ds_read_b128 v[230:233], v201 offset:5120
	ds_read_b128 v[234:237], v201 offset:6144
	ds_read_b128 v[238:241], v201 offset:7168
	global_load_lds_dwordx4 v[178:179], off
	v_lshl_add_u64 v[178:179], s[12:13], 0, v[168:169]
	s_add_i32 m0, s56, 0xe000
	s_nop 0
	global_load_lds_dwordx4 v[178:179], off
	s_waitcnt vmcnt(8)
	s_waitcnt lgkmcnt(0)
	s_barrier
	s_setprio 1
	s_waitcnt lgkmcnt(0)
	v_mfma_f32_16x16x32_bf16 v[126:129], v[130:133], v[210:213], 0
	v_mfma_f32_16x16x32_bf16 v[126:129], v[134:137], v[214:217], v[126:129]
	v_mfma_f32_16x16x32_bf16 v[122:125], v[138:141], v[210:213], 0
	v_mfma_f32_16x16x32_bf16 v[122:125], v[142:145], v[214:217], v[122:125]
	v_mfma_f32_16x16x32_bf16 v[110:113], v[130:133], v[218:221], 0
	v_mfma_f32_16x16x32_bf16 v[110:113], v[134:137], v[222:225], v[110:113]
	v_mfma_f32_16x16x32_bf16 v[106:109], v[138:141], v[218:221], 0
	v_mfma_f32_16x16x32_bf16 v[106:109], v[142:145], v[222:225], v[106:109]
	v_mfma_f32_16x16x32_bf16 v[94:97], v[130:133], v[226:229], 0
	v_mfma_f32_16x16x32_bf16 v[94:97], v[134:137], v[230:233], v[94:97]
	v_mfma_f32_16x16x32_bf16 v[90:93], v[138:141], v[226:229], 0
	v_mfma_f32_16x16x32_bf16 v[90:93], v[142:145], v[230:233], v[90:93]
	v_mfma_f32_16x16x32_bf16 v[78:81], v[130:133], v[234:237], 0
	v_mfma_f32_16x16x32_bf16 v[78:81], v[134:137], v[238:241], v[78:81]
	v_mfma_f32_16x16x32_bf16 v[74:77], v[138:141], v[234:237], 0
	v_mfma_f32_16x16x32_bf16 v[74:77], v[142:145], v[238:241], v[74:77]
	v_mfma_f32_16x16x32_bf16 v[118:121], v[170:173], v[210:213], 0
	v_mfma_f32_16x16x32_bf16 v[118:121], v[174:177], v[214:217], v[118:121]
	v_mfma_f32_16x16x32_bf16 v[114:117], v[202:205], v[210:213], 0
	v_mfma_f32_16x16x32_bf16 v[114:117], v[206:209], v[214:217], v[114:117]
	v_mfma_f32_16x16x32_bf16 v[102:105], v[170:173], v[218:221], 0
	v_mfma_f32_16x16x32_bf16 v[102:105], v[174:177], v[222:225], v[102:105]
	v_mfma_f32_16x16x32_bf16 v[98:101], v[202:205], v[218:221], 0
	v_mfma_f32_16x16x32_bf16 v[98:101], v[206:209], v[222:225], v[98:101]
	v_mfma_f32_16x16x32_bf16 v[86:89], v[170:173], v[226:229], 0
	v_mfma_f32_16x16x32_bf16 v[86:89], v[174:177], v[230:233], v[86:89]
	v_mfma_f32_16x16x32_bf16 v[82:85], v[202:205], v[226:229], 0
	v_mfma_f32_16x16x32_bf16 v[82:85], v[206:209], v[230:233], v[82:85]
	v_mfma_f32_16x16x32_bf16 v[70:73], v[170:173], v[234:237], 0
	v_mfma_f32_16x16x32_bf16 v[70:73], v[174:177], v[238:241], v[70:73]
	v_mfma_f32_16x16x32_bf16 v[66:69], v[202:205], v[234:237], 0
	v_mfma_f32_16x16x32_bf16 v[66:69], v[206:209], v[238:241], v[66:69]
	s_setprio 0
	s_barrier
	s_add_i32 s75, s75, s23
	v_lshl_add_u64 v[178:179], vcc, 0, v[0:1]
	s_mov_b32 m0, s75
	ds_read_b128 v[210:213], v201 offset:16384
	ds_read_b128 v[214:217], v201 offset:17408
	ds_read_b128 v[218:221], v201 offset:18432
	ds_read_b128 v[222:225], v201 offset:19456
	ds_read_b128 v[226:229], v201 offset:20480
	ds_read_b128 v[230:233], v201 offset:21504
	ds_read_b128 v[234:237], v201 offset:22528
	ds_read_b128 v[238:241], v201 offset:23552
	global_load_lds_dwordx4 v[178:179], off
	s_add_i32 m0, s75, 0x2000
	v_lshl_add_u64 v[242:243], vcc, 0, v[162:163]
	s_add_u32 vcc_lo, vcc_lo, s84
	s_addc_u32 vcc_hi, vcc_hi, 0
	s_add_i32 s43, s43, s23
	global_load_lds_dwordx4 v[242:243], off
	v_lshl_add_u64 v[244:245], vcc, 0, v[0:1]
	s_mov_b32 m0, s43
	v_lshl_add_u64 v[246:247], vcc, 0, v[162:163]
	global_load_lds_dwordx4 v[244:245], off
	s_add_i32 m0, s43, 0x2000
	v_lshl_add_u64 v[248:249], s[14:15], 0, v[158:159]
	global_load_lds_dwordx4 v[246:247], off
	s_mov_b32 m0, s56
	v_lshl_add_u64 v[250:251], s[14:15], 0, v[160:161]
	global_load_lds_dwordx4 v[248:249], off
	s_mov_b32 m0, s82
	s_nop 0
	global_load_lds_dwordx4 v[250:251], off
	s_waitcnt vmcnt(8)
	s_waitcnt lgkmcnt(0)
	s_barrier
; #define PG8_STAGE(bufoff, gbase, voff) do { _Pragma("unroll") for (int _i = 0; _i < 2; ++_i) \
;         __builtin_amdgcn_global_load_lds((const unsigned*)((const char*)(gbase) + (voff)[_i]), (PG8_LAS unsigned*)(lds + (bufoff) + ldsw + _i * 8192), 16, 0, 0); } while (0)
; #define PG8_LDA(dst, b, h) do { _Pragma("unroll") for (int m = 0; m < 4; ++m) _Pragma("unroll") for (int k = 0; k < 2; ++k) dst[m][k] = *(const PG8_LAS bf16x8*)(lds + PG8_SA(b, h) + aoff + m * 2048 + k * 1024); } while (0)
; #define PG8_LDB(dst, b, h) do { _Pragma("unroll") for (int n = 0; n < 2; ++n) _Pragma("unroll") for (int k = 0; k < 2; ++k) dst[n][k] = *(const PG8_LAS bf16x8*)(lds + PG8_SB(b, h) + boff + n * 2048 + k * 1024); } while (0)
; #define PG8_MMA(ai, bj, At, Bt) do { __builtin_amdgcn_s_setprio(1); _Pragma("unroll") for (int m = 0; m < 4; ++m) _Pragma("unroll") for (int n = 0; n < 2; ++n) _Pragma("unroll") for (int k = 0; k < 2; ++k) \
;         acc[ai][bj][m][n] = __builtin_amdgcn_mfma_f32_16x16x32_bf16(Bt[n][k], At[m][k], acc[ai][bj][m][n], 0, 0, 0); __builtin_amdgcn_s_setprio(0); } while (0)
; #define PG8_WAIT_V(n) asm volatile("s_waitcnt vmcnt(" #n ")" ::: "memory")
; template <class Epi, class Sched, bool ALIGN_EPI = false, bool SP2 = false>
; __device__ __forceinline__ void gemm_phase(PG8_LAS unsigned char* lds, const Gemm g, const Sched& S, const Epi& E) {
;     ...
;             PG8_LDB(B0, 0, 0); PG8_LDB(B1, 0, 1); PG8_SCHED; PG8_LDA(At, 0, 0); PG8_STAGE(PG8_SA(1, 1), a1 + hstep, voffA);
;             PG8_WAIT_V(8); PG8_WAIT_L(0); PG8_BAR; PG8_MMA(0, 0, At, B0); PG8_MMA(0, 1, At, B1); PG8_BAR; PG8_SCHED;
;             PG8_LDA(At, 0, 1); PG8_STAGE(PG8_SB(0, 0), b2, voffB); PG8_STAGE(PG8_SB(0, 1), b2 + hstep, voffB); PG8_STAGE(PG8_SA(0, 0), a2, voffA);
;             PG8_WAIT_V(8); PG8_WAIT_L(0); PG8_BAR; PG8_MMA(1, 0, At, B0); PG8_MMA(1, 1, At, B1); PG8_BAR; PG8_SCHED;
;             PG8_LDB(B0, 1, 0); PG8_LDB(B1, 1, 1); PG8_SCHED; PG8_LDA(At, 1, 0); PG8_STAGE(PG8_SA(0, 1), a2 + hstep, voffA);
;             PG8_WAIT_V(8); PG8_WAIT_L(0); PG8_BAR; PG8_MMA(0, 0, At, B0); PG8_MMA(0, 1, At, B1); PG8_BAR; PG8_SCHED;
;             PG8_LDA(At, 1, 1); PG8_STAGE(PG8_SB(1, 0), b3, voffB); PG8_STAGE(PG8_SB(1, 1), b3 + hstep, voffB); PG8_STAGE(PG8_SA(1, 0), a3, voffA);
;             PG8_WAIT_V(8); PG8_WAIT_L(0); PG8_BAR; PG8_MMA(1, 0, At, B0); PG8_MMA(1, 1, At, B1); PG8_BAR; PG8_SCHED;
	s_setprio 1
	s_waitcnt lgkmcnt(0)
	v_mfma_f32_16x16x32_bf16 v[62:65], v[130:133], v[210:213], 0
	v_mfma_f32_16x16x32_bf16 v[62:65], v[134:137], v[214:217], v[62:65]
	v_mfma_f32_16x16x32_bf16 v[58:61], v[138:141], v[210:213], 0
	v_mfma_f32_16x16x32_bf16 v[58:61], v[142:145], v[214:217], v[58:61]
	v_mfma_f32_16x16x32_bf16 v[46:49], v[130:133], v[218:221], 0
	v_mfma_f32_16x16x32_bf16 v[46:49], v[134:137], v[222:225], v[46:49]
	v_mfma_f32_16x16x32_bf16 v[42:45], v[138:141], v[218:221], 0
	v_mfma_f32_16x16x32_bf16 v[42:45], v[142:145], v[222:225], v[42:45]
	v_mfma_f32_16x16x32_bf16 v[30:33], v[130:133], v[226:229], 0
	v_mfma_f32_16x16x32_bf16 v[30:33], v[134:137], v[230:233], v[30:33]
	v_mfma_f32_16x16x32_bf16 v[26:29], v[138:141], v[226:229], 0
	v_mfma_f32_16x16x32_bf16 v[26:29], v[142:145], v[230:233], v[26:29]
	v_mfma_f32_16x16x32_bf16 v[14:17], v[130:133], v[234:237], 0
	v_mfma_f32_16x16x32_bf16 v[14:17], v[134:137], v[238:241], v[14:17]
	v_mfma_f32_16x16x32_bf16 v[10:13], v[138:141], v[234:237], 0
	v_mfma_f32_16x16x32_bf16 v[10:13], v[142:145], v[238:241], v[10:13]
	v_mfma_f32_16x16x32_bf16 v[54:57], v[170:173], v[210:213], 0
	v_mfma_f32_16x16x32_bf16 v[54:57], v[174:177], v[214:217], v[54:57]
	v_mfma_f32_16x16x32_bf16 v[50:53], v[202:205], v[210:213], 0
	v_mfma_f32_16x16x32_bf16 v[50:53], v[206:209], v[214:217], v[50:53]
	v_mfma_f32_16x16x32_bf16 v[38:41], v[170:173], v[218:221], 0
	v_mfma_f32_16x16x32_bf16 v[38:41], v[174:177], v[222:225], v[38:41]
	v_mfma_f32_16x16x32_bf16 v[34:37], v[202:205], v[218:221], 0
	v_mfma_f32_16x16x32_bf16 v[34:37], v[206:209], v[222:225], v[34:37]
	v_mfma_f32_16x16x32_bf16 v[22:25], v[170:173], v[226:229], 0
	v_mfma_f32_16x16x32_bf16 v[22:25], v[174:177], v[230:233], v[22:25]
	v_mfma_f32_16x16x32_bf16 v[18:21], v[202:205], v[226:229], 0
	v_mfma_f32_16x16x32_bf16 v[18:21], v[206:209], v[230:233], v[18:21]
	v_mfma_f32_16x16x32_bf16 v[6:9], v[170:173], v[234:237], 0
	v_mfma_f32_16x16x32_bf16 v[6:9], v[174:177], v[238:241], v[6:9]
	v_mfma_f32_16x16x32_bf16 v[2:5], v[202:205], v[234:237], 0
	v_mfma_f32_16x16x32_bf16 v[2:5], v[206:209], v[238:241], v[2:5]
	s_setprio 0
	s_barrier
	s_add_i32 s43, 0, 0x18000
	s_add_i32 s75, 0, 0x1c000
	v_add_u32_e32 v142, s43, v199
	v_add_u32_e32 v206, s75, v199
	ds_read_b128 v[130:133], v142
	ds_read_b128 v[134:137], v142 offset:1024
	ds_read_b128 v[138:141], v142 offset:2048
	ds_read_b128 v[142:145], v142 offset:3072
	ds_read_b128 v[170:173], v206
	ds_read_b128 v[174:177], v206 offset:1024
	ds_read_b128 v[202:205], v206 offset:2048
	ds_read_b128 v[206:209], v206 offset:3072
	s_add_u32 s14, s14, s84
	s_addc_u32 s15, s15, 0
	s_mov_b32 m0, s83
	v_lshl_add_u64 v[252:253], s[14:15], 0, v[158:159]
	ds_read_b128 v[210:213], v201 offset:32768
	ds_read_b128 v[214:217], v201 offset:33792
	ds_read_b128 v[218:221], v201 offset:34816
	ds_read_b128 v[222:225], v201 offset:35840
	ds_read_b128 v[226:229], v201 offset:36864
	ds_read_b128 v[230:233], v201 offset:37888
	ds_read_b128 v[234:237], v201 offset:38912
	ds_read_b128 v[238:241], v201 offset:39936
	global_load_lds_dwordx4 v[252:253], off
	v_lshl_add_u64 v[252:253], s[14:15], 0, v[160:161]
	s_mov_b32 m0, s24
	s_nop 0
	global_load_lds_dwordx4 v[252:253], off
	s_waitcnt vmcnt(8)
	s_waitcnt lgkmcnt(0)
	s_barrier
	s_setprio 1
	s_waitcnt lgkmcnt(0)
	v_mfma_f32_16x16x32_bf16 v[126:129], v[130:133], v[210:213], v[126:129]
	v_mfma_f32_16x16x32_bf16 v[126:129], v[134:137], v[214:217], v[126:129]
	v_mfma_f32_16x16x32_bf16 v[122:125], v[138:141], v[210:213], v[122:125]
	v_mfma_f32_16x16x32_bf16 v[122:125], v[142:145], v[214:217], v[122:125]
	v_mfma_f32_16x16x32_bf16 v[110:113], v[130:133], v[218:221], v[110:113]
	v_mfma_f32_16x16x32_bf16 v[110:113], v[134:137], v[222:225], v[110:113]
	v_mfma_f32_16x16x32_bf16 v[106:109], v[138:141], v[218:221], v[106:109]
	v_mfma_f32_16x16x32_bf16 v[106:109], v[142:145], v[222:225], v[106:109]
	v_mfma_f32_16x16x32_bf16 v[94:97], v[130:133], v[226:229], v[94:97]
	v_mfma_f32_16x16x32_bf16 v[94:97], v[134:137], v[230:233], v[94:97]
	v_mfma_f32_16x16x32_bf16 v[90:93], v[138:141], v[226:229], v[90:93]
	v_mfma_f32_16x16x32_bf16 v[90:93], v[142:145], v[230:233], v[90:93]
	v_mfma_f32_16x16x32_bf16 v[78:81], v[130:133], v[234:237], v[78:81]
	v_mfma_f32_16x16x32_bf16 v[78:81], v[134:137], v[238:241], v[78:81]
	v_mfma_f32_16x16x32_bf16 v[74:77], v[138:141], v[234:237], v[74:77]
	v_mfma_f32_16x16x32_bf16 v[74:77], v[142:145], v[238:241], v[74:77]
	v_mfma_f32_16x16x32_bf16 v[118:121], v[170:173], v[210:213], v[118:121]
	v_mfma_f32_16x16x32_bf16 v[118:121], v[174:177], v[214:217], v[118:121]
	v_mfma_f32_16x16x32_bf16 v[114:117], v[202:205], v[210:213], v[114:117]
	v_mfma_f32_16x16x32_bf16 v[114:117], v[206:209], v[214:217], v[114:117]
	v_mfma_f32_16x16x32_bf16 v[102:105], v[170:173], v[218:221], v[102:105]
	v_mfma_f32_16x16x32_bf16 v[102:105], v[174:177], v[222:225], v[102:105]
	v_mfma_f32_16x16x32_bf16 v[98:101], v[202:205], v[218:221], v[98:101]
	v_mfma_f32_16x16x32_bf16 v[98:101], v[206:209], v[222:225], v[98:101]
	v_mfma_f32_16x16x32_bf16 v[86:89], v[170:173], v[226:229], v[86:89]
	v_mfma_f32_16x16x32_bf16 v[86:89], v[174:177], v[230:233], v[86:89]
	v_mfma_f32_16x16x32_bf16 v[82:85], v[202:205], v[226:229], v[82:85]
	v_mfma_f32_16x16x32_bf16 v[82:85], v[206:209], v[230:233], v[82:85]
	v_mfma_f32_16x16x32_bf16 v[70:73], v[170:173], v[234:237], v[70:73]
	v_mfma_f32_16x16x32_bf16 v[70:73], v[174:177], v[238:241], v[70:73]
	v_mfma_f32_16x16x32_bf16 v[66:69], v[202:205], v[234:237], v[66:69]
	v_mfma_f32_16x16x32_bf16 v[66:69], v[206:209], v[238:241], v[66:69]
	s_setprio 0
	s_barrier
; #define PG8_STAGE(bufoff, gbase, voff) do { _Pragma("unroll") for (int _i = 0; _i < 2; ++_i) \
;         __builtin_amdgcn_global_load_lds((const unsigned*)((const char*)(gbase) + (voff)[_i]), (PG8_LAS unsigned*)(lds + (bufoff) + ldsw + _i * 8192), 16, 0, 0); } while (0)
; #define PG8_LDA(dst, b, h) do { _Pragma("unroll") for (int m = 0; m < 4; ++m) _Pragma("unroll") for (int k = 0; k < 2; ++k) dst[m][k] = *(const PG8_LAS bf16x8*)(lds + PG8_SA(b, h) + aoff + m * 2048 + k * 1024); } while (0)
; #define PG8_LDB(dst, b, h) do { _Pragma("unroll") for (int n = 0; n < 2; ++n) _Pragma("unroll") for (int k = 0; k < 2; ++k) dst[n][k] = *(const PG8_LAS bf16x8*)(lds + PG8_SB(b, h) + boff + n * 2048 + k * 1024); } while (0)
; template <class Epi, class Sched, bool ALIGN_EPI = false, bool SP2 = false>
; __device__ __forceinline__ void gemm_phase(PG8_LAS unsigned char* lds, const Gemm g, const Sched& S, const Epi& E) {
;     ...
;         for (int t = 0; t < nt; t += 2) {
;             const bool last = (t == nt - 2);
;             const char* a1 = cA + (size_t)(t + 1) * kstep;
;             const char* a2 = last ? nA : cA + (size_t)(t + 2) * kstep; const char* b2 = last ? nB : cB + (size_t)(t + 2) * kstep;
;             const char* a3 = a2 + kstep; const char* b3 = b2 + kstep;
;             if (last && has_next) S.a_ready(nxt);
;             if constexpr (SP2) {
;             PG8_LDB(B0, 0, 0); PG8_LDB(B1, 0, 1); PG8_SCHED; PG8_LDA(At, 0, 0); PG8_STAGE(PG8_SA(1, 1), a1 + hstep, voffA);
;             PG8_WAIT_V(8); PG8_WAIT_L(0); PG8_BAR; PG8_MMA(0, 0, At, B0); PG8_MMA(0, 1, At, B1); PG8_BAR; PG8_SCHED;
;             PG8_LDA(At, 0, 1); PG8_STAGE(PG8_SB(0, 0), b2, voffB); PG8_STAGE(PG8_SB(0, 1), b2 + hstep, voffB); PG8_STAGE(PG8_SA(0, 0), a2, voffA);
;             PG8_WAIT_V(8); PG8_WAIT_L(0); PG8_BAR; PG8_MMA(1, 0, At, B0); PG8_MMA(1, 1, At, B1); PG8_BAR; PG8_SCHED;
;             PG8_LDB(B0, 1, 0); PG8_LDB(B1, 1, 1); PG8_SCHED; PG8_LDA(At, 1, 0); PG8_STAGE(PG8_SA(0, 1), a2 + hstep, voffA);
;             PG8_WAIT_V(8); PG8_WAIT_L(0); PG8_BAR; PG8_MMA(0, 0, At, B0); PG8_MMA(0, 1, At, B1); PG8_BAR; PG8_SCHED;
;             PG8_LDA(At, 1, 1); PG8_STAGE(PG8_SB(1, 0), b3, voffB); PG8_STAGE(PG8_SB(1, 1), b3 + hstep, voffB); PG8_STAGE(PG8_SA(1, 0), a3, voffA);
;             PG8_WAIT_V(8); PG8_WAIT_L(0); PG8_BAR; PG8_MMA(1, 0, At, B0); PG8_MMA(1, 1, At, B1); PG8_BAR; PG8_SCHED;
	s_add_i32 s14, s43, s23
	v_lshl_add_u64 v[178:179], v[178:179], 0, s[94:95]
	s_mov_b32 m0, s14
	ds_read_b128 v[210:213], v201 offset:49152
	ds_read_b128 v[214:217], v201 offset:50176
	ds_read_b128 v[218:221], v201 offset:51200
	ds_read_b128 v[222:225], v201 offset:52224
	ds_read_b128 v[226:229], v201 offset:53248
	ds_read_b128 v[230:233], v201 offset:54272
	ds_read_b128 v[234:237], v201 offset:55296
	ds_read_b128 v[238:241], v201 offset:56320
	global_load_lds_dwordx4 v[178:179], off
	v_lshl_add_u64 v[178:179], v[242:243], 0, s[94:95]
	s_add_i32 m0, s14, 0x2000
	s_add_i32 s14, s75, s23
	global_load_lds_dwordx4 v[178:179], off
	v_lshl_add_u64 v[178:179], v[244:245], 0, s[94:95]
	s_mov_b32 m0, s14
	s_nop 0
	global_load_lds_dwordx4 v[178:179], off
	v_lshl_add_u64 v[178:179], v[246:247], 0, s[94:95]
	s_add_i32 m0, s14, 0x2000
	s_nop 0
	global_load_lds_dwordx4 v[178:179], off
	v_lshl_add_u64 v[178:179], v[248:249], 0, s[94:95]
	s_mov_b32 m0, s63
	s_nop 0
	global_load_lds_dwordx4 v[178:179], off
	v_lshl_add_u64 v[178:179], v[250:251], 0, s[94:95]
	s_mov_b32 m0, s70
	s_nop 0
	global_load_lds_dwordx4 v[178:179], off
	s_waitcnt vmcnt(8)
	s_waitcnt lgkmcnt(0)
	s_barrier
	s_setprio 1
	s_waitcnt lgkmcnt(0)
	v_mfma_f32_16x16x32_bf16 v[62:65], v[130:133], v[210:213], v[62:65]
	v_mfma_f32_16x16x32_bf16 v[62:65], v[134:137], v[214:217], v[62:65]
	v_mfma_f32_16x16x32_bf16 v[58:61], v[138:141], v[210:213], v[58:61]
	v_mfma_f32_16x16x32_bf16 v[58:61], v[142:145], v[214:217], v[58:61]
	v_mfma_f32_16x16x32_bf16 v[46:49], v[130:133], v[218:221], v[46:49]
	v_mfma_f32_16x16x32_bf16 v[46:49], v[134:137], v[222:225], v[46:49]
	v_mfma_f32_16x16x32_bf16 v[42:45], v[138:141], v[218:221], v[42:45]
	v_mfma_f32_16x16x32_bf16 v[42:45], v[142:145], v[222:225], v[42:45]
	v_mfma_f32_16x16x32_bf16 v[30:33], v[130:133], v[226:229], v[30:33]
	v_mfma_f32_16x16x32_bf16 v[30:33], v[134:137], v[230:233], v[30:33]
	v_mfma_f32_16x16x32_bf16 v[26:29], v[138:141], v[226:229], v[26:29]
	v_mfma_f32_16x16x32_bf16 v[26:29], v[142:145], v[230:233], v[26:29]
	v_mfma_f32_16x16x32_bf16 v[14:17], v[130:133], v[234:237], v[14:17]
	v_mfma_f32_16x16x32_bf16 v[14:17], v[134:137], v[238:241], v[14:17]
	v_mfma_f32_16x16x32_bf16 v[10:13], v[138:141], v[234:237], v[10:13]
	v_mfma_f32_16x16x32_bf16 v[10:13], v[142:145], v[238:241], v[10:13]
	v_mfma_f32_16x16x32_bf16 v[54:57], v[170:173], v[210:213], v[54:57]
	v_mfma_f32_16x16x32_bf16 v[54:57], v[174:177], v[214:217], v[54:57]
	v_mfma_f32_16x16x32_bf16 v[50:53], v[202:205], v[210:213], v[50:53]
	v_mfma_f32_16x16x32_bf16 v[50:53], v[206:209], v[214:217], v[50:53]
	v_mfma_f32_16x16x32_bf16 v[38:41], v[170:173], v[218:221], v[38:41]
	v_mfma_f32_16x16x32_bf16 v[38:41], v[174:177], v[222:225], v[38:41]
	v_mfma_f32_16x16x32_bf16 v[34:37], v[202:205], v[218:221], v[34:37]
	v_mfma_f32_16x16x32_bf16 v[34:37], v[206:209], v[222:225], v[34:37]
	v_mfma_f32_16x16x32_bf16 v[22:25], v[170:173], v[226:229], v[22:25]
	v_mfma_f32_16x16x32_bf16 v[22:25], v[174:177], v[230:233], v[22:25]
	v_mfma_f32_16x16x32_bf16 v[18:21], v[202:205], v[226:229], v[18:21]
	v_mfma_f32_16x16x32_bf16 v[18:21], v[206:209], v[230:233], v[18:21]
	v_mfma_f32_16x16x32_bf16 v[6:9], v[170:173], v[234:237], v[6:9]
	v_mfma_f32_16x16x32_bf16 v[6:9], v[174:177], v[238:241], v[6:9]
	v_mfma_f32_16x16x32_bf16 v[2:5], v[202:205], v[234:237], v[2:5]
	v_mfma_f32_16x16x32_bf16 v[2:5], v[206:209], v[238:241], v[2:5]
	s_setprio 0
	s_barrier
	s_add_u32 s12, s12, 0x100
	s_addc_u32 s13, s13, 0
	s_add_u32 s16, s16, 0x100
	s_addc_u32 s17, s17, 0
	s_cmp_ge_u32 s42, s28
	s_mov_b32 s14, s42
	s_cbranch_scc0 .LBB0_322
	s_branch .Lk_done
.LBB0_322:
	s_add_i32 s42, s14, 2
	s_add_u32 s43, s12, 0x80
	s_addc_u32 s15, s13, 0
	s_add_i32 s75, 0, 0x10000
	s_cmp_eq_u32 s25, s14
	s_cselect_b32 s15, s55, s15
	s_cselect_b32 s14, s54, s43
	s_cselect_b32 vcc_hi, s65, s17
	s_cselect_b32 vcc_lo, s64, s16
	s_add_i32 s43, 0, 0x14000
	v_add_u32_e32 v142, s75, v199
	v_add_u32_e32 v178, s43, v199
	ds_read_b128 v[130:133], v142
	ds_read_b128 v[134:137], v142 offset:1024
	ds_read_b128 v[138:141], v142 offset:2048
	ds_read_b128 v[142:145], v142 offset:3072
	ds_read_b128 v[170:173], v178
	ds_read_b128 v[174:177], v178 offset:1024
	ds_read_b128 v[202:205], v178 offset:2048
	ds_read_b128 v[206:209], v178 offset:3072
	v_lshl_add_u64 v[178:179], s[12:13], 0, v[166:167]
	s_add_i32 m0, s56, 0xc000
	ds_read_b128 v[210:213], v201
	ds_read_b128 v[214:217], v201 offset:1024
	ds_read_b128 v[218:221], v201 offset:2048
	ds_read_b128 v[222:225], v201 offset:3072
	ds_read_b128 v[226:229], v201 offset:4096
	ds_read_b128 v[230:233], v201 offset:5120
	ds_read_b128 v[234:237], v201 offset:6144
	ds_read_b128 v[238:241], v201 offset:7168
	global_load_lds_dwordx4 v[178:179], off
	v_lshl_add_u64 v[178:179], s[12:13], 0, v[168:169]
	s_add_i32 m0, s56, 0xe000
	s_nop 0
	global_load_lds_dwordx4 v[178:179], off
	s_waitcnt vmcnt(8)
	s_waitcnt lgkmcnt(0)
	s_barrier
; #define PG8_STAGE(bufoff, gbase, voff) do { _Pragma("unroll") for (int _i = 0; _i < 2; ++_i) \
;         __builtin_amdgcn_global_load_lds((const unsigned*)((const char*)(gbase) + (voff)[_i]), (PG8_LAS unsigned*)(lds + (bufoff) + ldsw + _i * 8192), 16, 0, 0); } while (0)
; #define PG8_LDA(dst, b, h) do { _Pragma("unroll") for (int m = 0; m < 4; ++m) _Pragma("unroll") for (int k = 0; k < 2; ++k) dst[m][k] = *(const PG8_LAS bf16x8*)(lds + PG8_SA(b, h) + aoff + m * 2048 + k * 1024); } while (0)
; #define PG8_LDB(dst, b, h) do { _Pragma("unroll") for (int n = 0; n < 2; ++n) _Pragma("unroll") for (int k = 0; k < 2; ++k) dst[n][k] = *(const PG8_LAS bf16x8*)(lds + PG8_SB(b, h) + boff + n * 2048 + k * 1024); } while (0)
; #define PG8_MMA(ai, bj, At, Bt) do { __builtin_amdgcn_s_setprio(1); _Pragma("unroll") for (int m = 0; m < 4; ++m) _Pragma("unroll") for (int n = 0; n < 2; ++n) _Pragma("unroll") for (int k = 0; k < 2; ++k) \
;         acc[ai][bj][m][n] = __builtin_amdgcn_mfma_f32_16x16x32_bf16(Bt[n][k], At[m][k], acc[ai][bj][m][n], 0, 0, 0); __builtin_amdgcn_s_setprio(0); } while (0)
; #define PG8_WAIT_V(n) asm volatile("s_waitcnt vmcnt(" #n ")" ::: "memory")
; template <class Epi, class Sched, bool ALIGN_EPI = false, bool SP2 = false>
; __device__ __forceinline__ void gemm_phase(PG8_LAS unsigned char* lds, const Gemm g, const Sched& S, const Epi& E) {
;     ...
;             PG8_LDB(B0, 0, 0); PG8_LDB(B1, 0, 1); PG8_SCHED; PG8_LDA(At, 0, 0); PG8_STAGE(PG8_SA(1, 1), a1 + hstep, voffA);
;             PG8_WAIT_V(8); PG8_WAIT_L(0); PG8_BAR; PG8_MMA(0, 0, At, B0); PG8_MMA(0, 1, At, B1); PG8_BAR; PG8_SCHED;
;             PG8_LDA(At, 0, 1); PG8_STAGE(PG8_SB(0, 0), b2, voffB); PG8_STAGE(PG8_SB(0, 1), b2 + hstep, voffB); PG8_STAGE(PG8_SA(0, 0), a2, voffA);
;             PG8_WAIT_V(8); PG8_WAIT_L(0); PG8_BAR; PG8_MMA(1, 0, At, B0); PG8_MMA(1, 1, At, B1); PG8_BAR; PG8_SCHED;
;             PG8_LDB(B0, 1, 0); PG8_LDB(B1, 1, 1); PG8_SCHED; PG8_LDA(At, 1, 0); PG8_STAGE(PG8_SA(0, 1), a2 + hstep, voffA);
;             PG8_WAIT_V(8); PG8_WAIT_L(0); PG8_BAR; PG8_MMA(0, 0, At, B0); PG8_MMA(0, 1, At, B1); PG8_BAR; PG8_SCHED;
;             PG8_LDA(At, 1, 1); PG8_STAGE(PG8_SB(1, 0), b3, voffB); PG8_STAGE(PG8_SB(1, 1), b3 + hstep, voffB); PG8_STAGE(PG8_SA(1, 0), a3, voffA);
;             PG8_WAIT_V(8); PG8_WAIT_L(0); PG8_BAR; PG8_MMA(1, 0, At, B0); PG8_MMA(1, 1, At, B1); PG8_BAR; PG8_SCHED;
	s_setprio 1
	s_waitcnt lgkmcnt(0)
	v_mfma_f32_16x16x32_bf16 v[126:129], v[130:133], v[210:213], v[126:129]
	v_mfma_f32_16x16x32_bf16 v[126:129], v[134:137], v[214:217], v[126:129]
	v_mfma_f32_16x16x32_bf16 v[122:125], v[138:141], v[210:213], v[122:125]
	v_mfma_f32_16x16x32_bf16 v[122:125], v[142:145], v[214:217], v[122:125]
	v_mfma_f32_16x16x32_bf16 v[110:113], v[130:133], v[218:221], v[110:113]
	v_mfma_f32_16x16x32_bf16 v[110:113], v[134:137], v[222:225], v[110:113]
	v_mfma_f32_16x16x32_bf16 v[106:109], v[138:141], v[218:221], v[106:109]
	v_mfma_f32_16x16x32_bf16 v[106:109], v[142:145], v[222:225], v[106:109]
	v_mfma_f32_16x16x32_bf16 v[94:97], v[130:133], v[226:229], v[94:97]
	v_mfma_f32_16x16x32_bf16 v[94:97], v[134:137], v[230:233], v[94:97]
	v_mfma_f32_16x16x32_bf16 v[90:93], v[138:141], v[226:229], v[90:93]
	v_mfma_f32_16x16x32_bf16 v[90:93], v[142:145], v[230:233], v[90:93]
	v_mfma_f32_16x16x32_bf16 v[78:81], v[130:133], v[234:237], v[78:81]
	v_mfma_f32_16x16x32_bf16 v[78:81], v[134:137], v[238:241], v[78:81]
	v_mfma_f32_16x16x32_bf16 v[74:77], v[138:141], v[234:237], v[74:77]
	v_mfma_f32_16x16x32_bf16 v[74:77], v[142:145], v[238:241], v[74:77]
	v_mfma_f32_16x16x32_bf16 v[118:121], v[170:173], v[210:213], v[118:121]
	v_mfma_f32_16x16x32_bf16 v[118:121], v[174:177], v[214:217], v[118:121]
	v_mfma_f32_16x16x32_bf16 v[114:117], v[202:205], v[210:213], v[114:117]
	v_mfma_f32_16x16x32_bf16 v[114:117], v[206:209], v[214:217], v[114:117]
	v_mfma_f32_16x16x32_bf16 v[102:105], v[170:173], v[218:221], v[102:105]
	v_mfma_f32_16x16x32_bf16 v[102:105], v[174:177], v[222:225], v[102:105]
	v_mfma_f32_16x16x32_bf16 v[98:101], v[202:205], v[218:221], v[98:101]
	v_mfma_f32_16x16x32_bf16 v[98:101], v[206:209], v[222:225], v[98:101]
	v_mfma_f32_16x16x32_bf16 v[86:89], v[170:173], v[226:229], v[86:89]
	v_mfma_f32_16x16x32_bf16 v[86:89], v[174:177], v[230:233], v[86:89]
	v_mfma_f32_16x16x32_bf16 v[82:85], v[202:205], v[226:229], v[82:85]
	v_mfma_f32_16x16x32_bf16 v[82:85], v[206:209], v[230:233], v[82:85]
	v_mfma_f32_16x16x32_bf16 v[70:73], v[170:173], v[234:237], v[70:73]
	v_mfma_f32_16x16x32_bf16 v[70:73], v[174:177], v[238:241], v[70:73]
	v_mfma_f32_16x16x32_bf16 v[66:69], v[202:205], v[234:237], v[66:69]
	v_mfma_f32_16x16x32_bf16 v[66:69], v[206:209], v[238:241], v[66:69]
	s_setprio 0
	s_barrier
	s_add_i32 s75, s75, s23
	v_lshl_add_u64 v[178:179], vcc, 0, v[0:1]
	s_mov_b32 m0, s75
	ds_read_b128 v[210:213], v201 offset:16384
	ds_read_b128 v[214:217], v201 offset:17408
	ds_read_b128 v[218:221], v201 offset:18432
	ds_read_b128 v[222:225], v201 offset:19456
	ds_read_b128 v[226:229], v201 offset:20480
	ds_read_b128 v[230:233], v201 offset:21504
	ds_read_b128 v[234:237], v201 offset:22528
	ds_read_b128 v[238:241], v201 offset:23552
	global_load_lds_dwordx4 v[178:179], off
	s_add_i32 m0, s75, 0x2000
	v_lshl_add_u64 v[242:243], vcc, 0, v[162:163]
	s_add_u32 vcc_lo, vcc_lo, s84
	s_addc_u32 vcc_hi, vcc_hi, 0
	s_add_i32 s43, s43, s23
	global_load_lds_dwordx4 v[242:243], off
	v_lshl_add_u64 v[244:245], vcc, 0, v[0:1]
	s_mov_b32 m0, s43
	v_lshl_add_u64 v[246:247], vcc, 0, v[162:163]
	global_load_lds_dwordx4 v[244:245], off
	s_add_i32 m0, s43, 0x2000
	v_lshl_add_u64 v[248:249], s[14:15], 0, v[158:159]
	global_load_lds_dwordx4 v[246:247], off
	s_mov_b32 m0, s56
	v_lshl_add_u64 v[250:251], s[14:15], 0, v[160:161]
	global_load_lds_dwordx4 v[248:249], off
	s_mov_b32 m0, s82
	s_nop 0
	global_load_lds_dwordx4 v[250:251], off
	s_waitcnt vmcnt(8)
	s_waitcnt lgkmcnt(0)
	s_barrier
	s_setprio 1
	s_waitcnt lgkmcnt(0)
	v_mfma_f32_16x16x32_bf16 v[62:65], v[130:133], v[210:213], v[62:65]
	v_mfma_f32_16x16x32_bf16 v[62:65], v[134:137], v[214:217], v[62:65]
	v_mfma_f32_16x16x32_bf16 v[58:61], v[138:141], v[210:213], v[58:61]
	v_mfma_f32_16x16x32_bf16 v[58:61], v[142:145], v[214:217], v[58:61]
	v_mfma_f32_16x16x32_bf16 v[46:49], v[130:133], v[218:221], v[46:49]
	v_mfma_f32_16x16x32_bf16 v[46:49], v[134:137], v[222:225], v[46:49]
	v_mfma_f32_16x16x32_bf16 v[42:45], v[138:141], v[218:221], v[42:45]
	v_mfma_f32_16x16x32_bf16 v[42:45], v[142:145], v[222:225], v[42:45]
	v_mfma_f32_16x16x32_bf16 v[30:33], v[130:133], v[226:229], v[30:33]
	v_mfma_f32_16x16x32_bf16 v[30:33], v[134:137], v[230:233], v[30:33]
	v_mfma_f32_16x16x32_bf16 v[26:29], v[138:141], v[226:229], v[26:29]
	v_mfma_f32_16x16x32_bf16 v[26:29], v[142:145], v[230:233], v[26:29]
	v_mfma_f32_16x16x32_bf16 v[14:17], v[130:133], v[234:237], v[14:17]
	v_mfma_f32_16x16x32_bf16 v[14:17], v[134:137], v[238:241], v[14:17]
	v_mfma_f32_16x16x32_bf16 v[10:13], v[138:141], v[234:237], v[10:13]
	v_mfma_f32_16x16x32_bf16 v[10:13], v[142:145], v[238:241], v[10:13]
	v_mfma_f32_16x16x32_bf16 v[54:57], v[170:173], v[210:213], v[54:57]
	v_mfma_f32_16x16x32_bf16 v[54:57], v[174:177], v[214:217], v[54:57]
	v_mfma_f32_16x16x32_bf16 v[50:53], v[202:205], v[210:213], v[50:53]
	v_mfma_f32_16x16x32_bf16 v[50:53], v[206:209], v[214:217], v[50:53]
	v_mfma_f32_16x16x32_bf16 v[38:41], v[170:173], v[218:221], v[38:41]
	v_mfma_f32_16x16x32_bf16 v[38:41], v[174:177], v[222:225], v[38:41]
	v_mfma_f32_16x16x32_bf16 v[34:37], v[202:205], v[218:221], v[34:37]
	v_mfma_f32_16x16x32_bf16 v[34:37], v[206:209], v[222:225], v[34:37]
	v_mfma_f32_16x16x32_bf16 v[22:25], v[170:173], v[226:229], v[22:25]
	v_mfma_f32_16x16x32_bf16 v[22:25], v[174:177], v[230:233], v[22:25]
	v_mfma_f32_16x16x32_bf16 v[18:21], v[202:205], v[226:229], v[18:21]
	v_mfma_f32_16x16x32_bf16 v[18:21], v[206:209], v[230:233], v[18:21]
	v_mfma_f32_16x16x32_bf16 v[6:9], v[170:173], v[234:237], v[6:9]
	v_mfma_f32_16x16x32_bf16 v[6:9], v[174:177], v[238:241], v[6:9]
	v_mfma_f32_16x16x32_bf16 v[2:5], v[202:205], v[234:237], v[2:5]
	v_mfma_f32_16x16x32_bf16 v[2:5], v[206:209], v[238:241], v[2:5]
	s_setprio 0
	s_barrier
; #define PG8_STAGE(bufoff, gbase, voff) do { _Pragma("unroll") for (int _i = 0; _i < 2; ++_i) \
;         __builtin_amdgcn_global_load_lds((const unsigned*)((const char*)(gbase) + (voff)[_i]), (PG8_LAS unsigned*)(lds + (bufoff) + ldsw + _i * 8192), 16, 0, 0); } while (0)
; #define PG8_LDA(dst, b, h) do { _Pragma("unroll") for (int m = 0; m < 4; ++m) _Pragma("unroll") for (int k = 0; k < 2; ++k) dst[m][k] = *(const PG8_LAS bf16x8*)(lds + PG8_SA(b, h) + aoff + m * 2048 + k * 1024); } while (0)
; #define PG8_LDB(dst, b, h) do { _Pragma("unroll") for (int n = 0; n < 2; ++n) _Pragma("unroll") for (int k = 0; k < 2; ++k) dst[n][k] = *(const PG8_LAS bf16x8*)(lds + PG8_SB(b, h) + boff + n * 2048 + k * 1024); } while (0)
; #define PG8_MMA(ai, bj, At, Bt) do { __builtin_amdgcn_s_setprio(1); _Pragma("unroll") for (int m = 0; m < 4; ++m) _Pragma("unroll") for (int n = 0; n < 2; ++n) _Pragma("unroll") for (int k = 0; k < 2; ++k) \
;         acc[ai][bj][m][n] = __builtin_amdgcn_mfma_f32_16x16x32_bf16(Bt[n][k], At[m][k], acc[ai][bj][m][n], 0, 0, 0); __builtin_amdgcn_s_setprio(0); } while (0)
; #define PG8_WAIT_V(n) asm volatile("s_waitcnt vmcnt(" #n ")" ::: "memory")
; template <class Epi, class Sched, bool ALIGN_EPI = false, bool SP2 = false>
; __device__ __forceinline__ void gemm_phase(PG8_LAS unsigned char* lds, const Gemm g, const Sched& S, const Epi& E) {
;     ...
;             PG8_LDB(B0, 0, 0); PG8_LDB(B1, 0, 1); PG8_SCHED; PG8_LDA(At, 0, 0); PG8_STAGE(PG8_SA(1, 1), a1 + hstep, voffA);
;             PG8_WAIT_V(8); PG8_WAIT_L(0); PG8_BAR; PG8_MMA(0, 0, At, B0); PG8_MMA(0, 1, At, B1); PG8_BAR; PG8_SCHED;
;             PG8_LDA(At, 0, 1); PG8_STAGE(PG8_SB(0, 0), b2, voffB); PG8_STAGE(PG8_SB(0, 1), b2 + hstep, voffB); PG8_STAGE(PG8_SA(0, 0), a2, voffA);
;             PG8_WAIT_V(8); PG8_WAIT_L(0); PG8_BAR; PG8_MMA(1, 0, At, B0); PG8_MMA(1, 1, At, B1); PG8_BAR; PG8_SCHED;
;             PG8_LDB(B0, 1, 0); PG8_LDB(B1, 1, 1); PG8_SCHED; PG8_LDA(At, 1, 0); PG8_STAGE(PG8_SA(0, 1), a2 + hstep, voffA);
;             PG8_WAIT_V(8); PG8_WAIT_L(0); PG8_BAR; PG8_MMA(0, 0, At, B0); PG8_MMA(0, 1, At, B1); PG8_BAR; PG8_SCHED;
;             PG8_LDA(At, 1, 1); PG8_STAGE(PG8_SB(1, 0), b3, voffB); PG8_STAGE(PG8_SB(1, 1), b3 + hstep, voffB); PG8_STAGE(PG8_SA(1, 0), a3, voffA);
;             PG8_WAIT_V(8); PG8_WAIT_L(0); PG8_BAR; PG8_MMA(1, 0, At, B0); PG8_MMA(1, 1, At, B1); PG8_BAR; PG8_SCHED;
	s_add_i32 s43, 0, 0x18000
	s_add_i32 s75, 0, 0x1c000
	v_add_u32_e32 v142, s43, v199
	v_add_u32_e32 v206, s75, v199
	ds_read_b128 v[130:133], v142
	ds_read_b128 v[134:137], v142 offset:1024
	ds_read_b128 v[138:141], v142 offset:2048
	ds_read_b128 v[142:145], v142 offset:3072
	ds_read_b128 v[170:173], v206
	ds_read_b128 v[174:177], v206 offset:1024
	ds_read_b128 v[202:205], v206 offset:2048
	ds_read_b128 v[206:209], v206 offset:3072
	s_add_u32 s14, s14, s84
	s_addc_u32 s15, s15, 0
	s_mov_b32 m0, s83
	v_lshl_add_u64 v[252:253], s[14:15], 0, v[158:159]
	ds_read_b128 v[210:213], v201 offset:32768
	ds_read_b128 v[214:217], v201 offset:33792
	ds_read_b128 v[218:221], v201 offset:34816
	ds_read_b128 v[222:225], v201 offset:35840
	ds_read_b128 v[226:229], v201 offset:36864
	ds_read_b128 v[230:233], v201 offset:37888
	ds_read_b128 v[234:237], v201 offset:38912
	ds_read_b128 v[238:241], v201 offset:39936
	global_load_lds_dwordx4 v[252:253], off
	v_lshl_add_u64 v[252:253], s[14:15], 0, v[160:161]
	s_mov_b32 m0, s24
	s_nop 0
	global_load_lds_dwordx4 v[252:253], off
	s_waitcnt vmcnt(8)
	s_waitcnt lgkmcnt(0)
	s_barrier
	s_setprio 1
	s_waitcnt lgkmcnt(0)
	v_mfma_f32_16x16x32_bf16 v[126:129], v[130:133], v[210:213], v[126:129]
	v_mfma_f32_16x16x32_bf16 v[126:129], v[134:137], v[214:217], v[126:129]
	v_mfma_f32_16x16x32_bf16 v[122:125], v[138:141], v[210:213], v[122:125]
	v_mfma_f32_16x16x32_bf16 v[122:125], v[142:145], v[214:217], v[122:125]
	v_mfma_f32_16x16x32_bf16 v[110:113], v[130:133], v[218:221], v[110:113]
	v_mfma_f32_16x16x32_bf16 v[110:113], v[134:137], v[222:225], v[110:113]
	v_mfma_f32_16x16x32_bf16 v[106:109], v[138:141], v[218:221], v[106:109]
	v_mfma_f32_16x16x32_bf16 v[106:109], v[142:145], v[222:225], v[106:109]
	v_mfma_f32_16x16x32_bf16 v[94:97], v[130:133], v[226:229], v[94:97]
	v_mfma_f32_16x16x32_bf16 v[94:97], v[134:137], v[230:233], v[94:97]
	v_mfma_f32_16x16x32_bf16 v[90:93], v[138:141], v[226:229], v[90:93]
	v_mfma_f32_16x16x32_bf16 v[90:93], v[142:145], v[230:233], v[90:93]
	v_mfma_f32_16x16x32_bf16 v[78:81], v[130:133], v[234:237], v[78:81]
	v_mfma_f32_16x16x32_bf16 v[78:81], v[134:137], v[238:241], v[78:81]
	v_mfma_f32_16x16x32_bf16 v[74:77], v[138:141], v[234:237], v[74:77]
	v_mfma_f32_16x16x32_bf16 v[74:77], v[142:145], v[238:241], v[74:77]
	v_mfma_f32_16x16x32_bf16 v[118:121], v[170:173], v[210:213], v[118:121]
	v_mfma_f32_16x16x32_bf16 v[118:121], v[174:177], v[214:217], v[118:121]
	v_mfma_f32_16x16x32_bf16 v[114:117], v[202:205], v[210:213], v[114:117]
	v_mfma_f32_16x16x32_bf16 v[114:117], v[206:209], v[214:217], v[114:117]
	v_mfma_f32_16x16x32_bf16 v[102:105], v[170:173], v[218:221], v[102:105]
	v_mfma_f32_16x16x32_bf16 v[102:105], v[174:177], v[222:225], v[102:105]
	v_mfma_f32_16x16x32_bf16 v[98:101], v[202:205], v[218:221], v[98:101]
	v_mfma_f32_16x16x32_bf16 v[98:101], v[206:209], v[222:225], v[98:101]
	v_mfma_f32_16x16x32_bf16 v[86:89], v[170:173], v[226:229], v[86:89]
	v_mfma_f32_16x16x32_bf16 v[86:89], v[174:177], v[230:233], v[86:89]
	v_mfma_f32_16x16x32_bf16 v[82:85], v[202:205], v[226:229], v[82:85]
	v_mfma_f32_16x16x32_bf16 v[82:85], v[206:209], v[230:233], v[82:85]
	v_mfma_f32_16x16x32_bf16 v[70:73], v[170:173], v[234:237], v[70:73]
	v_mfma_f32_16x16x32_bf16 v[70:73], v[174:177], v[238:241], v[70:73]
	v_mfma_f32_16x16x32_bf16 v[66:69], v[202:205], v[234:237], v[66:69]
	v_mfma_f32_16x16x32_bf16 v[66:69], v[206:209], v[238:241], v[66:69]
	s_setprio 0
	s_barrier
; #define PG8_STAGE(bufoff, gbase, voff) do { _Pragma("unroll") for (int _i = 0; _i < 2; ++_i) \
;         __builtin_amdgcn_global_load_lds((const unsigned*)((const char*)(gbase) + (voff)[_i]), (PG8_LAS unsigned*)(lds + (bufoff) + ldsw + _i * 8192), 16, 0, 0); } while (0)
; #define PG8_LDA(dst, b, h) do { _Pragma("unroll") for (int m = 0; m < 4; ++m) _Pragma("unroll") for (int k = 0; k < 2; ++k) dst[m][k] = *(const PG8_LAS bf16x8*)(lds + PG8_SA(b, h) + aoff + m * 2048 + k * 1024); } while (0)
; #define PG8_LDB(dst, b, h) do { _Pragma("unroll") for (int n = 0; n < 2; ++n) _Pragma("unroll") for (int k = 0; k < 2; ++k) dst[n][k] = *(const PG8_LAS bf16x8*)(lds + PG8_SB(b, h) + boff + n * 2048 + k * 1024); } while (0)
; #define PG8_MMA(ai, bj, At, Bt) do { __builtin_amdgcn_s_setprio(1); _Pragma("unroll") for (int m = 0; m < 4; ++m) _Pragma("unroll") for (int n = 0; n < 2; ++n) _Pragma("unroll") for (int k = 0; k < 2; ++k) \
;         acc[ai][bj][m][n] = __builtin_amdgcn_mfma_f32_16x16x32_bf16(Bt[n][k], At[m][k], acc[ai][bj][m][n], 0, 0, 0); __builtin_amdgcn_s_setprio(0); } while (0)
; #define PG8_WAIT_V(n) asm volatile("s_waitcnt vmcnt(" #n ")" ::: "memory")
; template <class Epi, class Sched, bool ALIGN_EPI = false, bool SP2 = false>
; __device__ __forceinline__ void gemm_phase(PG8_LAS unsigned char* lds, const Gemm g, const Sched& S, const Epi& E) {
;     ...
;             PG8_LDB(B0, 0, 0); PG8_LDB(B1, 0, 1); PG8_SCHED; PG8_LDA(At, 0, 0); PG8_STAGE(PG8_SA(1, 1), a1 + hstep, voffA);
;             PG8_WAIT_V(8); PG8_WAIT_L(0); PG8_BAR; PG8_MMA(0, 0, At, B0); PG8_MMA(0, 1, At, B1); PG8_BAR; PG8_SCHED;
;             PG8_LDA(At, 0, 1); PG8_STAGE(PG8_SB(0, 0), b2, voffB); PG8_STAGE(PG8_SB(0, 1), b2 + hstep, voffB); PG8_STAGE(PG8_SA(0, 0), a2, voffA);
;             PG8_WAIT_V(8); PG8_WAIT_L(0); PG8_BAR; PG8_MMA(1, 0, At, B0); PG8_MMA(1, 1, At, B1); PG8_BAR; PG8_SCHED;
;             PG8_LDB(B0, 1, 0); PG8_LDB(B1, 1, 1); PG8_SCHED; PG8_LDA(At, 1, 0); PG8_STAGE(PG8_SA(0, 1), a2 + hstep, voffA);
;             PG8_WAIT_V(8); PG8_WAIT_L(0); PG8_BAR; PG8_MMA(0, 0, At, B0); PG8_MMA(0, 1, At, B1); PG8_BAR; PG8_SCHED;
;             PG8_LDA(At, 1, 1); PG8_STAGE(PG8_SB(1, 0), b3, voffB); PG8_STAGE(PG8_SB(1, 1), b3 + hstep, voffB); PG8_STAGE(PG8_SA(1, 0), a3, voffA);
;             PG8_WAIT_V(8); PG8_WAIT_L(0); PG8_BAR; PG8_MMA(1, 0, At, B0); PG8_MMA(1, 1, At, B1); PG8_BAR; PG8_SCHED;
	s_add_i32 s14, s43, s23
	v_lshl_add_u64 v[178:179], v[178:179], 0, s[94:95]
	s_mov_b32 m0, s14
	ds_read_b128 v[210:213], v201 offset:49152
	ds_read_b128 v[214:217], v201 offset:50176
	ds_read_b128 v[218:221], v201 offset:51200
	ds_read_b128 v[222:225], v201 offset:52224
	ds_read_b128 v[226:229], v201 offset:53248
	ds_read_b128 v[230:233], v201 offset:54272
	ds_read_b128 v[234:237], v201 offset:55296
	ds_read_b128 v[238:241], v201 offset:56320
	global_load_lds_dwordx4 v[178:179], off
	v_lshl_add_u64 v[178:179], v[242:243], 0, s[94:95]
	s_add_i32 m0, s14, 0x2000
	s_add_i32 s14, s75, s23
	global_load_lds_dwordx4 v[178:179], off
	v_lshl_add_u64 v[178:179], v[244:245], 0, s[94:95]
	s_mov_b32 m0, s14
	s_nop 0
	global_load_lds_dwordx4 v[178:179], off
	v_lshl_add_u64 v[178:179], v[246:247], 0, s[94:95]
	s_add_i32 m0, s14, 0x2000
	s_nop 0
	global_load_lds_dwordx4 v[178:179], off
	v_lshl_add_u64 v[178:179], v[248:249], 0, s[94:95]
	s_mov_b32 m0, s63
	s_nop 0
	global_load_lds_dwordx4 v[178:179], off
	v_lshl_add_u64 v[178:179], v[250:251], 0, s[94:95]
	s_mov_b32 m0, s70
	s_nop 0
	global_load_lds_dwordx4 v[178:179], off
	s_waitcnt vmcnt(8)
	s_waitcnt lgkmcnt(0)
	s_barrier
	s_setprio 1
	s_waitcnt lgkmcnt(0)
	v_mfma_f32_16x16x32_bf16 v[62:65], v[130:133], v[210:213], v[62:65]
	v_mfma_f32_16x16x32_bf16 v[62:65], v[134:137], v[214:217], v[62:65]
	v_mfma_f32_16x16x32_bf16 v[58:61], v[138:141], v[210:213], v[58:61]
	v_mfma_f32_16x16x32_bf16 v[58:61], v[142:145], v[214:217], v[58:61]
	v_mfma_f32_16x16x32_bf16 v[46:49], v[130:133], v[218:221], v[46:49]
	v_mfma_f32_16x16x32_bf16 v[46:49], v[134:137], v[222:225], v[46:49]
	v_mfma_f32_16x16x32_bf16 v[42:45], v[138:141], v[218:221], v[42:45]
	v_mfma_f32_16x16x32_bf16 v[42:45], v[142:145], v[222:225], v[42:45]
	v_mfma_f32_16x16x32_bf16 v[30:33], v[130:133], v[226:229], v[30:33]
	v_mfma_f32_16x16x32_bf16 v[30:33], v[134:137], v[230:233], v[30:33]
	v_mfma_f32_16x16x32_bf16 v[26:29], v[138:141], v[226:229], v[26:29]
	v_mfma_f32_16x16x32_bf16 v[26:29], v[142:145], v[230:233], v[26:29]
	v_mfma_f32_16x16x32_bf16 v[14:17], v[130:133], v[234:237], v[14:17]
	v_mfma_f32_16x16x32_bf16 v[14:17], v[134:137], v[238:241], v[14:17]
	v_mfma_f32_16x16x32_bf16 v[10:13], v[138:141], v[234:237], v[10:13]
	v_mfma_f32_16x16x32_bf16 v[10:13], v[142:145], v[238:241], v[10:13]
	v_mfma_f32_16x16x32_bf16 v[54:57], v[170:173], v[210:213], v[54:57]
	v_mfma_f32_16x16x32_bf16 v[54:57], v[174:177], v[214:217], v[54:57]
	v_mfma_f32_16x16x32_bf16 v[50:53], v[202:205], v[210:213], v[50:53]
	v_mfma_f32_16x16x32_bf16 v[50:53], v[206:209], v[214:217], v[50:53]
	v_mfma_f32_16x16x32_bf16 v[38:41], v[170:173], v[218:221], v[38:41]
	v_mfma_f32_16x16x32_bf16 v[38:41], v[174:177], v[222:225], v[38:41]
	v_mfma_f32_16x16x32_bf16 v[34:37], v[202:205], v[218:221], v[34:37]
	v_mfma_f32_16x16x32_bf16 v[34:37], v[206:209], v[222:225], v[34:37]
	v_mfma_f32_16x16x32_bf16 v[22:25], v[170:173], v[226:229], v[22:25]
	v_mfma_f32_16x16x32_bf16 v[22:25], v[174:177], v[230:233], v[22:25]
	v_mfma_f32_16x16x32_bf16 v[18:21], v[202:205], v[226:229], v[18:21]
	v_mfma_f32_16x16x32_bf16 v[18:21], v[206:209], v[230:233], v[18:21]
	v_mfma_f32_16x16x32_bf16 v[6:9], v[170:173], v[234:237], v[6:9]
	v_mfma_f32_16x16x32_bf16 v[6:9], v[174:177], v[238:241], v[6:9]
	v_mfma_f32_16x16x32_bf16 v[2:5], v[202:205], v[234:237], v[2:5]
	v_mfma_f32_16x16x32_bf16 v[2:5], v[206:209], v[238:241], v[2:5]
	s_setprio 0
	s_barrier
	s_add_u32 s12, s12, 0x100
	s_addc_u32 s13, s13, 0
	s_add_u32 s16, s16, 0x100
	s_addc_u32 s17, s17, 0
	s_cmp_ge_u32 s42, s28
	s_mov_b32 s14, s42
	s_cbranch_scc0 .LBB0_322
